# 4-workgroup panel barriers (posted atomic + sc1 poll, bounded) replace the grid barrier after the gate GEMM and after the up-merge (panel-local producer/consumer sets, write-through outputs)
# speedup vs baseline: 1.0878x; 1.0021x over previous
.LBB0_571:
	s_cmp_ge_i32 s70, s71
	s_mov_b64 s[2:3], -1
	s_cbranch_scc1 .LBB0_23
	s_cmp_eq_u32 s70, 5
	s_cbranch_scc1 .Lpb_entry
	s_cmp_eq_u32 s70, 6
	s_cbranch_scc1 .Lpb_entry
	s_cmp_eq_u32 s70, 12
	s_cbranch_scc1 .Lpb_entry
	s_cmp_eq_u32 s70, 13
	s_cbranch_scc1 .Lpb_entry
	s_branch .LBB0_580
.Lpb_entry:
	s_waitcnt vmcnt(0)
	s_barrier
	s_mov_b64 s[4:5], exec
	v_readlane_b32 s2, v254, 9
	v_readlane_b32 s3, v254, 10
	s_nop 1
	s_and_b64 s[2:3], s[4:5], s[2:3]
	s_mov_b64 exec, s[2:3]
	s_cbranch_execz .LBB0_22
	buffer_inv sc1
	v_readlane_b32 s6, v254, 0
	v_readlane_b32 s8, v254, 11
	v_readlane_b32 s9, v254, 12
	s_nop 1
	s_and_b32 s7, s6, 7
	s_lshl_b32 s7, s7, 3
	s_bfe_u32 s6, s6, 0x30003
	s_add_i32 s7, s7, s6
	s_lshl_b32 s7, s7, 2
	s_addk_i32 s7, 0x300
	s_add_u32 s8, s8, s7
	s_addc_u32 s9, s9, 0
	s_sub_i32 s6, s70, 4
	s_cmp_gt_i32 s70, 7
	s_cbranch_scc0 .Lpb_target
	s_sub_i32 s6, s70, 9
.Lpb_target:
	s_lshl_b32 s6, s6, 2
	s_mov_b32 s10, 0
	s_nop 4
	global_atomic_add v177, v209, s[8:9]
.Lpb_spin:
	global_load_dword v0, v177, s[8:9] sc1
	s_waitcnt vmcnt(0)
	v_readfirstlane_b32 s7, v0
	s_nop 1
	s_cmp_ge_u32 s7, s6
	s_cbranch_scc1 .LBB0_22
	s_sleep 1
	s_add_i32 s10, s10, 1
	s_cmp_lt_u32 s10, 0x8000
	s_cbranch_scc1 .Lpb_spin
	s_branch .LBB0_22
